# seq-DFT phase: 512 units of 128x128 (one big + one small per workgroup), 4-slot LDS ring K-loop with DMA inside MFMA segment, XCD-aware unit deal
# speedup vs baseline: 1.0877x; 1.0137x over previous
.LBB0_160:
	s_and_b64 vcc, exec, s[4:5]
	s_cbranch_vccz .LBB0_265
	s_waitcnt lgkmcnt(0)
	v_readlane_b32 s42, v239, 29
	s_cmp_gt_i32 s80, 0
	s_mov_b64 s[4:5], -1
	v_readlane_b32 s43, v239, 30
	s_cbranch_scc0 .LBB0_263
	s_cmp_gt_i32 s80, 1
	s_cbranch_scc0 .LBB0_227
	v_readlane_b32 s6, v239, 49
	v_readlane_b32 s7, v239, 50
	s_and_b64 vcc, exec, s[6:7]
	s_cbranch_vccz .LBB0_190
	s_cmpk_gt_i32 s78, 0xff
	v_readfirstlane_b32 s3, v210
	s_cbranch_scc1 .LBB0_189
	s_add_u32 s4, s42, 0x900000
	s_addc_u32 s5, s43, 0
	s_add_u32 s61, s42, 0xb00000
	s_addc_u32 s65, s43, 0
	s_add_u32 s66, s42, 0x10100000
	s_addc_u32 s67, s43, 0
	s_cmpk_gt_i32 s78, 0xff
	s_mov_b64 s[6:7], -1
	s_cbranch_scc0 .LBB0_167
	s_add_i32 s8, s78, 0xffffff00
	s_lshl_b32 s6, s8, 4
	s_and_b32 s70, s6, 0xffffff80
	s_and_b32 s50, s78, 7
	s_lshr_b32 s10, s8, 7
	s_mov_b32 s11, 0
	s_lshl_b32 s9, s50, 19
	s_lshl_b32 s6, s8, 5
	s_and_b32 s6, s6, 0xe00
	s_or_b32 s9, s9, s6
	s_lshl_b64 s[6:7], s[10:11], 22
	s_or_b32 s6, s6, s9
	s_lshl_b64 s[6:7], s[6:7], 1
	s_add_u32 s42, s66, s6
	s_addc_u32 s43, s67, s7
	s_bfe_u32 s8, s8, 0x10003
	s_lshl_b32 s8, s8, 20
	s_add_u32 s46, s4, s8
	s_addc_u32 s47, s5, 0
	s_mov_b32 s33, 8
	s_mov_b64 s[6:7], 0
.LBB0_167:
	s_andn2_b64 vcc, exec, s[6:7]
	s_mov_b32 s57, 0x48000
	s_cbranch_vccnz .LBB0_169
	s_and_b32 s8, s78, 7
	s_lshr_b32 s9, s78, 3
	s_lshr_b32 s7, s8, 1
	s_lshl_b32 s7, s7, 2
	s_and_b32 s6, s9, 3
	s_or_b32 s7, s7, s6
	s_and_b32 s6, s8, 1
	s_lshr_b32 s50, s9, 2
	s_lshl_b32 s8, s6, 11
	s_lshl_b32 s9, s7, 7
	s_or_b32 s8, s8, s9
	s_add_i32 s70, s8, 0x1000
	s_lshl_b32 s7, s7, 20
	s_add_u32 s46, s61, s7
	s_addc_u32 s47, s65, 0
	s_ashr_i32 s7, s6, 31
	s_lshl_b32 s8, s50, 20
	s_lshl_b64 s[6:7], s[6:7], 23
	s_add_u32 s6, s66, s6
	s_addc_u32 s7, s67, s7
	s_add_u32 s6, s6, s8
	s_addc_u32 s7, s7, 0
	s_add_u32 s42, s6, 0x1000000
	s_addc_u32 s43, s7, 0
	s_mov_b32 s33, 64
.LBB0_169:
	v_bfe_i32 v1, v210, 27, 1
	v_lshlrev_b32_e32 v3, 4, v210
	v_lshrrev_b32_e32 v1, 22, v1
	v_ashrrev_i32_e32 v0, 31, v210
	v_add_u32_e32 v1, v3, v1
	v_lshrrev_b32_e32 v0, 26, v0
	v_and_b32_e32 v1, 0xfffffc00, v1
	v_add_u32_e32 v0, v210, v0
	v_sub_u32_e32 v1, v3, v1
	v_ashrrev_i32_e32 v0, 6, v0
	v_lshrrev_b32_e32 v2, 4, v1
	v_bitop3_b32 v2, v2, v1, 32 bitop3:0x6c
	v_lshlrev_b32_e32 v1, 3, v0
	v_and_b32_e32 v4, -16, v1
	v_ashrrev_i32_e32 v1, 31, v2
	v_lshrrev_b32_e32 v1, 26, v1
	v_add_u32_e32 v5, v2, v1
	v_ashrrev_i32_e32 v1, 6, v5
	v_and_b32_e32 v5, 0xc0, v5
	v_sub_u32_e32 v2, v2, v5
	v_lshlrev_b32_e32 v6, 5, v0
	v_ashrrev_i16_sdwa v2, v198, sext(v2) dst_sel:DWORD dst_unused:UNUSED_PAD src0_sel:DWORD src1_sel:BYTE_0
	v_and_b32_e32 v6, 32, v6
	v_bfe_i32 v2, v2, 0, 16
	v_add_u32_e32 v4, v1, v4
	v_and_b32_e32 v8, 3, v1
	s_mov_b32 s7, 0x7ffe0
	v_add_lshl_u32 v6, v6, v2, 1
	v_lshlrev_b32_e32 v5, 1, v4
	v_lshrrev_b32_e32 v7, 2, v4
	v_and_or_b32 v8, v4, s7, v8
	v_lshl_add_u32 v64, v4, 13, v6
	v_add_u32_e32 v4, 0x2000, v3
	v_ashrrev_i32_e32 v3, 31, v4
	v_lshrrev_b32_e32 v3, 22, v3
	v_and_b32_e32 v5, 24, v5
	v_and_b32_e32 v7, 4, v7
	v_add_u32_e32 v3, v4, v3
	v_or3_b32 v5, v8, v7, v5
	v_ashrrev_i32_e32 v3, 10, v3
	v_lshl_add_u32 v164, v5, 13, v6
	v_mul_i32_i24_e32 v5, 0x400, v3
	v_sub_u32_e32 v4, v4, v5
	v_lshrrev_b32_e32 v5, 4, v4
	v_bitop3_b32 v5, v5, v4, 32 bitop3:0x6c
	v_lshlrev_b32_e32 v4, 3, v3
	v_and_b32_e32 v6, -16, v4
	v_ashrrev_i32_e32 v4, 31, v5
	v_lshrrev_b32_e32 v4, 26, v4
	v_add_u32_e32 v7, v5, v4
	v_ashrrev_i32_e32 v4, 6, v7
	v_add_u32_e32 v6, v4, v6
	v_and_b32_e32 v7, 0xc0, v7
	v_and_b32_e32 v10, 3, v4
	v_sub_u32_e32 v5, v5, v7
	v_and_or_b32 v10, v6, s7, v10
	s_ashr_i32 s7, s3, 6
	v_lshlrev_b32_e32 v8, 5, v3
	v_ashrrev_i16_sdwa v5, v198, sext(v5) dst_sel:DWORD dst_unused:UNUSED_PAD src0_sel:DWORD src1_sel:BYTE_0
	v_lshlrev_b32_e32 v7, 1, v6
	v_lshrrev_b32_e32 v9, 2, v6
	s_lshl_b32 s51, s7, 10
	v_and_b32_e32 v8, 32, v8
	v_bfe_i32 v5, v5, 0, 16
	v_and_b32_e32 v7, 24, v7
	v_and_b32_e32 v9, 4, v9
	s_add_i32 s68, s51, 0
	v_or3_b32 v7, v10, v9, v7
	v_add_lshl_u32 v8, v8, v5, 1
	s_add_i32 m0, s68, 0x10000
	v_lshl_add_u32 v68, v7, 13, v8
	global_load_lds_dwordx4 v164, s[42:43]
	s_add_i32 m0, s68, 0x12000
	s_add_i32 s69, s68, 0x14000
	global_load_lds_dwordx4 v68, s[42:43]
	s_add_i32 s71, s68, 0x16000
	s_ashr_i32 s6, s3, 8
	s_add_i32 s72, s68, 0x2000
	s_mov_b32 m0, s68
	s_add_u32 s8, s46, 0x100000
	v_lshl_add_u32 v66, v6, 13, v8
	global_load_lds_dwordx4 v64, s[46:47]
	s_mov_b32 m0, s72
	s_addc_u32 s9, s47, 0
	s_add_i32 s73, s68, 0x4000
	global_load_lds_dwordx4 v66, s[46:47]
	s_add_i32 s76, s68, 0x6000
	s_cmp_eq_u32 s6, 1
	s_cselect_b64 s[82:83], -1, 0
	s_cmp_lg_u32 s6, 1
	s_cbranch_scc1 .LBB0_171
	s_barrier
.LBB0_171:
	v_readlane_b32 s8, v239, 29
	v_lshl_add_u64 v[6:7], s[42:43], 0, v[164:165]
	v_mov_b32_e32 v69, v165
	v_readlane_b32 s9, v239, 30
	s_add_u32 s8, s8, 0x9900000
	v_lshl_add_u64 v[8:9], s[42:43], 0, v[68:69]
	v_mov_b32_e32 v65, v165
	s_addc_u32 s9, s9, 0
	s_add_i32 m0, s68, 0x18000
	v_lshl_add_u64 v[6:7], v[6:7], 0, s[0:1]
	v_lshl_add_u64 v[10:11], s[46:47], 0, v[64:65]
	v_mov_b32_e32 v67, v165
	s_waitcnt vmcnt(0)
	s_barrier
	global_load_lds_dwordx4 v[6:7], off
	v_lshl_add_u64 v[8:9], v[8:9], 0, s[0:1]
	s_add_i32 m0, s68, 0x1a000
	s_add_i32 s89, s68, 0x8000
	v_lshl_add_u64 v[12:13], s[46:47], 0, v[66:67]
	global_load_lds_dwordx4 v[8:9], off
	v_lshl_add_u64 v[10:11], v[10:11], 0, s[0:1]
	s_mov_b32 m0, s89
	s_add_i32 s90, s68, 0xa000
	global_load_lds_dwordx4 v[10:11], off
	v_lshl_add_u64 v[10:11], v[12:13], 0, s[0:1]
	s_mov_b32 m0, s90
	s_add_i32 s91, s68, 0x1c000
	global_load_lds_dwordx4 v[10:11], off
	s_add_i32 m0, s68, 0x13f00
	s_nop 0
	global_load_lds_dwordx4 v164, s[42:43] offset:256
	s_add_i32 m0, s68, 0x15f00
	s_nop 0
	global_load_lds_dwordx4 v68, s[42:43] offset:256
	s_add_i32 m0, s68, 0x3f00
	s_nop 0
	global_load_lds_dwordx4 v64, s[46:47] offset:256
	s_add_i32 m0, s68, 0x5f00
	s_nop 0
	global_load_lds_dwordx4 v66, s[46:47] offset:256
	s_add_i32 s97, s68, 0x1e000
	v_and_b32_e32 v14, 48, v211
	v_lshlrev_b32_e32 v15, 6, v211
	s_movk_i32 s10, 0x3c0
	v_lshlrev_b32_e32 v6, 16, v3
	v_and_or_b32 v14, v15, s10, v14
	v_lshlrev_b32_e32 v15, 2, v211
	v_and_b32_e32 v6, 0xfffe0000, v6
	s_lshl_b32 s77, s6, 6
	s_lshl_b32 s6, s6, 13
	v_and_b32_e32 v15, 32, v15
	v_lshl_add_u32 v4, v4, 13, v6
	v_and_b32_e32 v3, 1, v3
	v_bitop3_b32 v16, v14, s6, v15 bitop3:0xde
	s_lshl_b32 s6, s7, 5
	v_lshl_or_b32 v3, v3, 6, v4
	s_and_b32 s6, s6, 0x60
	v_lshl_add_u32 v70, v5, 1, v3
	v_lshlrev_b32_e32 v3, 16, v0
	s_lshl_b32 s7, s6, 7
	v_and_b32_e32 v3, 0xfffe0000, v3
	s_waitcnt vmcnt(8)
	s_cmpk_lt_u32 s3, 0x100
	v_lshl_add_u32 v1, v1, 13, v3
	v_and_b32_e32 v0, 1, v0
	v_readlane_b32 s12, v240, 62
	s_cselect_b64 s[10:11], -1, 0
	v_lshl_or_b32 v0, v0, 6, v1
	v_readlane_b32 s13, v240, 63
	s_lshl_b32 s12, s6, 1
	v_bitop3_b32 v74, s7, v14, v15 bitop3:0xf6
	v_mov_b32_e32 v71, v165
	v_lshl_add_u32 v72, v2, 1, v0
	v_mov_b32_e32 v73, v165
	s_mov_b32 s3, 0
	v_add_u32_e32 v75, 0, v16
	v_writelane_b32 v240, s12, 62
	s_mov_b64 s[14:15], s[42:43]
	s_mov_b64 s[34:35], s[46:47]
	s_barrier
	v_writelane_b32 v240, s13, 63
	s_branch .LBB0_174

.LBB0_174:
	s_add_i32 s3, s3, 1
	s_mul_i32 s7, s3, s60
	s_add_i32 s7, s7, s78
	s_cmpk_lt_i32 s7, 0x200
	s_cselect_b64 s[18:19], -1, 0
	s_cmpk_gt_i32 s7, 0x1ff
	s_cbranch_scc1 .LBB0_179
	s_cmpk_gt_i32 s7, 0xff
	s_cbranch_scc0 .Lseq_next_big
	s_add_i32 s6, s7, 0xffffff00
	s_and_b32 s12, s7, 7
	s_lshl_b32 s13, s6, 4
	s_and_b32 s13, s13, 0xffffff80
	s_lshr_b32 s14, s6, 7
	s_mov_b32 s15, 0
	s_lshl_b32 s34, s12, 19
	s_lshl_b64 s[14:15], s[14:15], 22
	s_or_b32 s14, s14, s34
	s_lshl_b32 s34, s6, 5
	s_and_b32 s34, s34, 0xe00
	s_or_b32 s14, s14, s34
	s_lshl_b64 s[14:15], s[14:15], 1
	s_add_u32 s14, s66, s14
	s_addc_u32 s15, s67, s15
	s_bfe_u32 s6, s6, 0x10003
	s_lshl_b32 s6, s6, 20
	s_add_u32 s34, s4, s6
	s_addc_u32 s35, s5, 0
	s_mov_b32 s6, 8
	s_branch .LBB0_179
.Lseq_next_big:
	s_and_b32 s12, s7, 7
	s_lshr_b32 s13, s7, 3
	s_lshr_b32 s14, s12, 1
	s_lshl_b32 s14, s14, 2
	s_and_b32 s6, s13, 3
	s_or_b32 s14, s14, s6
	s_and_b32 s6, s12, 1
	s_lshr_b32 s12, s13, 2
	s_lshl_b32 s7, s6, 11
	s_lshl_b32 s13, s14, 7
	s_or_b32 s7, s7, s13
	s_add_i32 s13, s7, 0x1000
	s_lshl_b32 s7, s14, 20
	s_add_u32 s34, s61, s7
	s_addc_u32 s35, s65, 0
	s_ashr_i32 s7, s6, 31
	s_lshl_b32 s14, s12, 20
	s_lshl_b64 s[6:7], s[6:7], 23
	s_add_u32 s6, s66, s6
	s_addc_u32 s7, s67, s7
	s_add_u32 s6, s6, s14
	s_addc_u32 s7, s7, 0
	s_add_u32 s14, s6, 0x1000000
	s_addc_u32 s15, s7, 0
	s_mov_b32 s6, 64
.LBB0_179:
	s_cmp_lt_i32 s33, 1
	s_cbranch_scc1 .LBB0_187
	s_add_i32 s7, s33, -4
	s_add_u32 vcc_lo, s42, 0x180
	s_addc_u32 vcc_hi, s43, 0
	s_add_u32 s42, s46, 0x180
	v_mov_b32_e32 v0, 0
	s_addc_u32 s43, s47, 0
	s_mov_b32 s52, 0
	v_mov_b32_e32 v1, v0
	v_mov_b32_e32 v2, v0
	v_mov_b32_e32 v3, v0
	v_mov_b32_e32 v4, v0
	v_mov_b32_e32 v5, v0
	v_mov_b32_e32 v6, v0
	v_mov_b32_e32 v7, v0
	v_mov_b32_e32 v8, v0
	v_mov_b32_e32 v9, v0
	v_mov_b32_e32 v10, v0
	v_mov_b32_e32 v11, v0
	v_mov_b32_e32 v12, v0
	v_mov_b32_e32 v13, v0
	v_mov_b32_e32 v14, v0
	v_mov_b32_e32 v15, v0
	v_mov_b32_e32 v16, v0
	v_mov_b32_e32 v17, v0
	v_mov_b32_e32 v18, v0
	v_mov_b32_e32 v19, v0
	v_mov_b32_e32 v20, v0
	v_mov_b32_e32 v21, v0
	v_mov_b32_e32 v22, v0
	v_mov_b32_e32 v23, v0
	v_mov_b32_e32 v24, v0
	v_mov_b32_e32 v25, v0
	v_mov_b32_e32 v26, v0
	v_mov_b32_e32 v27, v0
	v_mov_b32_e32 v28, v0
	v_mov_b32_e32 v29, v0
	v_mov_b32_e32 v30, v0
	v_mov_b32_e32 v31, v0
	v_mov_b32_e32 v32, v0
	v_mov_b32_e32 v33, v0
	v_mov_b32_e32 v34, v0
	v_mov_b32_e32 v35, v0
	v_mov_b32_e32 v36, v0
	v_mov_b32_e32 v37, v0
	v_mov_b32_e32 v38, v0
	v_mov_b32_e32 v39, v0
	v_mov_b32_e32 v40, v0
	v_mov_b32_e32 v41, v0
	v_mov_b32_e32 v42, v0
	v_mov_b32_e32 v43, v0
	v_mov_b32_e32 v44, v0
	v_mov_b32_e32 v45, v0
	v_mov_b32_e32 v46, v0
	v_mov_b32_e32 v47, v0
	v_mov_b32_e32 v48, v0
	v_mov_b32_e32 v49, v0
	v_mov_b32_e32 v50, v0
	v_mov_b32_e32 v51, v0
	v_mov_b32_e32 v52, v0
	v_mov_b32_e32 v53, v0
	v_mov_b32_e32 v54, v0
	v_mov_b32_e32 v55, v0
	v_mov_b32_e32 v56, v0
	v_mov_b32_e32 v57, v0
	v_mov_b32_e32 v58, v0
	v_mov_b32_e32 v59, v0
	v_mov_b32_e32 v60, v0
	v_mov_b32_e32 v61, v0
	v_mov_b32_e32 v62, v0
	v_mov_b32_e32 v63, v0
.LBB0_181:
	v_add_u32_e32 v124, 0x10000, v74
	s_add_u32 s46, s42, 0x80
	s_addc_u32 s47, s43, 0
	s_add_u32 s54, vcc_lo, 0x80
	s_addc_u32 s55, vcc_hi, 0
	s_cmp_eq_u32 s7, s52
	s_cselect_b32 s46, s34, s46
	s_cselect_b32 s47, s35, s47
	s_cselect_b32 s54, s14, s54
	s_cselect_b32 s55, s15, s55
	ds_read_b128 v[76:79], v124
	ds_read_b128 v[80:83], v124 offset:1024
	ds_read_b128 v[84:87], v124 offset:2048
	ds_read_b128 v[88:91], v124 offset:3072
	ds_read_b128 v[92:95], v75
	ds_read_b128 v[96:99], v75 offset:1024
	ds_read_b128 v[100:103], v75 offset:2048
	ds_read_b128 v[104:107], v75 offset:3072
	ds_read_b128 v[108:111], v75 offset:4096
	ds_read_b128 v[112:115], v75 offset:5120
	ds_read_b128 v[116:119], v75 offset:6144
	ds_read_b128 v[120:123], v75 offset:7168
	s_waitcnt vmcnt(4)
	s_waitcnt lgkmcnt(0)
	s_barrier
	s_setprio 1
	v_mfma_f32_16x16x32_bf16 v[60:63], v[76:79], v[92:95], v[60:63]
	v_mfma_f32_16x16x32_bf16 v[56:59], v[84:87], v[92:95], v[56:59]
	s_add_i32 m0, s51, 0x1c000
	v_mfma_f32_16x16x32_bf16 v[52:55], v[76:79], v[100:103], v[52:55]
	global_load_lds_dwordx4 v164, vcc
	v_mfma_f32_16x16x32_bf16 v[48:51], v[84:87], v[100:103], v[48:51]
	v_mfma_f32_16x16x32_bf16 v[44:47], v[76:79], v[108:111], v[44:47]
	v_mfma_f32_16x16x32_bf16 v[40:43], v[84:87], v[108:111], v[40:43]
	s_add_i32 m0, s51, 0x1e000
	v_mfma_f32_16x16x32_bf16 v[36:39], v[76:79], v[116:119], v[36:39]
	global_load_lds_dwordx4 v68, vcc
	v_mfma_f32_16x16x32_bf16 v[32:35], v[84:87], v[116:119], v[32:35]
	v_mfma_f32_16x16x32_bf16 v[60:63], v[80:83], v[96:99], v[60:63]
	v_mfma_f32_16x16x32_bf16 v[56:59], v[88:91], v[96:99], v[56:59]
	s_add_i32 m0, s51, 0xc000
	v_mfma_f32_16x16x32_bf16 v[52:55], v[80:83], v[104:107], v[52:55]
	global_load_lds_dwordx4 v64, s[42:43]
	v_mfma_f32_16x16x32_bf16 v[48:51], v[88:91], v[104:107], v[48:51]
	v_mfma_f32_16x16x32_bf16 v[44:47], v[80:83], v[112:115], v[44:47]
	v_mfma_f32_16x16x32_bf16 v[40:43], v[88:91], v[112:115], v[40:43]
	s_add_i32 m0, s51, 0xe000
	v_mfma_f32_16x16x32_bf16 v[36:39], v[80:83], v[120:123], v[36:39]
	global_load_lds_dwordx4 v66, s[42:43]
	v_mfma_f32_16x16x32_bf16 v[32:35], v[88:91], v[120:123], v[32:35]
	s_setprio 0
	s_barrier
	ds_read_b128 v[76:79], v124 offset:32768
	ds_read_b128 v[80:83], v124 offset:33792
	ds_read_b128 v[84:87], v124 offset:34816
	ds_read_b128 v[88:91], v124 offset:35840
	ds_read_b128 v[92:95], v75 offset:32768
	ds_read_b128 v[96:99], v75 offset:33792
	ds_read_b128 v[100:103], v75 offset:34816
	ds_read_b128 v[104:107], v75 offset:35840
	ds_read_b128 v[108:111], v75 offset:36864
	ds_read_b128 v[112:115], v75 offset:37888
	ds_read_b128 v[116:119], v75 offset:38912
	ds_read_b128 v[120:123], v75 offset:39936
	s_waitcnt vmcnt(4)
	s_waitcnt lgkmcnt(0)
	s_barrier
	s_setprio 1
	v_mfma_f32_16x16x32_bf16 v[60:63], v[76:79], v[92:95], v[60:63]
	v_mfma_f32_16x16x32_bf16 v[56:59], v[84:87], v[92:95], v[56:59]
	s_add_i32 m0, s51, 0x10000
	v_mfma_f32_16x16x32_bf16 v[52:55], v[76:79], v[100:103], v[52:55]
	global_load_lds_dwordx4 v164, s[54:55]
	v_mfma_f32_16x16x32_bf16 v[48:51], v[84:87], v[100:103], v[48:51]
	v_mfma_f32_16x16x32_bf16 v[44:47], v[76:79], v[108:111], v[44:47]
	v_mfma_f32_16x16x32_bf16 v[40:43], v[84:87], v[108:111], v[40:43]
	s_add_i32 m0, s51, 0x12000
	v_mfma_f32_16x16x32_bf16 v[36:39], v[76:79], v[116:119], v[36:39]
	global_load_lds_dwordx4 v68, s[54:55]
	v_mfma_f32_16x16x32_bf16 v[32:35], v[84:87], v[116:119], v[32:35]
	v_mfma_f32_16x16x32_bf16 v[60:63], v[80:83], v[96:99], v[60:63]
	v_mfma_f32_16x16x32_bf16 v[56:59], v[88:91], v[96:99], v[56:59]
	s_add_i32 m0, s51, 0x0
	v_mfma_f32_16x16x32_bf16 v[52:55], v[80:83], v[104:107], v[52:55]
	global_load_lds_dwordx4 v64, s[46:47]
	v_mfma_f32_16x16x32_bf16 v[48:51], v[88:91], v[104:107], v[48:51]
	v_mfma_f32_16x16x32_bf16 v[44:47], v[80:83], v[112:115], v[44:47]
	v_mfma_f32_16x16x32_bf16 v[40:43], v[88:91], v[112:115], v[40:43]
	s_add_i32 m0, s51, 0x2000
	v_mfma_f32_16x16x32_bf16 v[36:39], v[80:83], v[120:123], v[36:39]
	global_load_lds_dwordx4 v66, s[46:47]
	v_mfma_f32_16x16x32_bf16 v[32:35], v[88:91], v[120:123], v[32:35]
	s_setprio 0
	s_barrier
	ds_read_b128 v[76:79], v124 offset:16384
	ds_read_b128 v[80:83], v124 offset:17408
	ds_read_b128 v[84:87], v124 offset:18432
	ds_read_b128 v[88:91], v124 offset:19456
	ds_read_b128 v[92:95], v75 offset:16384
	ds_read_b128 v[96:99], v75 offset:17408
	ds_read_b128 v[100:103], v75 offset:18432
	ds_read_b128 v[104:107], v75 offset:19456
	ds_read_b128 v[108:111], v75 offset:20480
	ds_read_b128 v[112:115], v75 offset:21504
	ds_read_b128 v[116:119], v75 offset:22528
	ds_read_b128 v[120:123], v75 offset:23552
	s_waitcnt vmcnt(4)
	s_waitcnt lgkmcnt(0)
	s_barrier
	s_setprio 1
	v_mfma_f32_16x16x32_bf16 v[60:63], v[76:79], v[92:95], v[60:63]
	v_mfma_f32_16x16x32_bf16 v[56:59], v[84:87], v[92:95], v[56:59]
	s_add_i32 m0, s51, 0x17f80
	v_mfma_f32_16x16x32_bf16 v[52:55], v[76:79], v[100:103], v[52:55]
	global_load_lds_dwordx4 v164, s[54:55] offset:128
	v_mfma_f32_16x16x32_bf16 v[48:51], v[84:87], v[100:103], v[48:51]
	v_mfma_f32_16x16x32_bf16 v[44:47], v[76:79], v[108:111], v[44:47]
	v_mfma_f32_16x16x32_bf16 v[40:43], v[84:87], v[108:111], v[40:43]
	s_add_i32 m0, s51, 0x19f80
	v_mfma_f32_16x16x32_bf16 v[36:39], v[76:79], v[116:119], v[36:39]
	global_load_lds_dwordx4 v68, s[54:55] offset:128
	v_mfma_f32_16x16x32_bf16 v[32:35], v[84:87], v[116:119], v[32:35]
	v_mfma_f32_16x16x32_bf16 v[60:63], v[80:83], v[96:99], v[60:63]
	v_mfma_f32_16x16x32_bf16 v[56:59], v[88:91], v[96:99], v[56:59]
	s_add_i32 m0, s51, 0x7f80
	v_mfma_f32_16x16x32_bf16 v[52:55], v[80:83], v[104:107], v[52:55]
	global_load_lds_dwordx4 v64, s[46:47] offset:128
	v_mfma_f32_16x16x32_bf16 v[48:51], v[88:91], v[104:107], v[48:51]
	v_mfma_f32_16x16x32_bf16 v[44:47], v[80:83], v[112:115], v[44:47]
	v_mfma_f32_16x16x32_bf16 v[40:43], v[88:91], v[112:115], v[40:43]
	s_add_i32 m0, s51, 0x9f80
	v_mfma_f32_16x16x32_bf16 v[36:39], v[80:83], v[120:123], v[36:39]
	global_load_lds_dwordx4 v66, s[46:47] offset:128
	v_mfma_f32_16x16x32_bf16 v[32:35], v[88:91], v[120:123], v[32:35]
	s_setprio 0
	s_barrier
	ds_read_b128 v[76:79], v124 offset:49152
	ds_read_b128 v[80:83], v124 offset:50176
	ds_read_b128 v[84:87], v124 offset:51200
	ds_read_b128 v[88:91], v124 offset:52224
	ds_read_b128 v[92:95], v75 offset:49152
	ds_read_b128 v[96:99], v75 offset:50176
	ds_read_b128 v[100:103], v75 offset:51200
	ds_read_b128 v[104:107], v75 offset:52224
	ds_read_b128 v[108:111], v75 offset:53248
	ds_read_b128 v[112:115], v75 offset:54272
	ds_read_b128 v[116:119], v75 offset:55296
	ds_read_b128 v[120:123], v75 offset:56320
	s_waitcnt vmcnt(4)
	s_waitcnt lgkmcnt(0)
	s_barrier
	s_setprio 1
	v_mfma_f32_16x16x32_bf16 v[60:63], v[76:79], v[92:95], v[60:63]
	v_mfma_f32_16x16x32_bf16 v[56:59], v[84:87], v[92:95], v[56:59]
	s_add_i32 m0, s51, 0x13f00
	v_mfma_f32_16x16x32_bf16 v[52:55], v[76:79], v[100:103], v[52:55]
	global_load_lds_dwordx4 v164, s[54:55] offset:256
	v_mfma_f32_16x16x32_bf16 v[48:51], v[84:87], v[100:103], v[48:51]
	v_mfma_f32_16x16x32_bf16 v[44:47], v[76:79], v[108:111], v[44:47]
	v_mfma_f32_16x16x32_bf16 v[40:43], v[84:87], v[108:111], v[40:43]
	s_add_i32 m0, s51, 0x15f00
	v_mfma_f32_16x16x32_bf16 v[36:39], v[76:79], v[116:119], v[36:39]
	global_load_lds_dwordx4 v68, s[54:55] offset:256
	v_mfma_f32_16x16x32_bf16 v[32:35], v[84:87], v[116:119], v[32:35]
	v_mfma_f32_16x16x32_bf16 v[60:63], v[80:83], v[96:99], v[60:63]
	v_mfma_f32_16x16x32_bf16 v[56:59], v[88:91], v[96:99], v[56:59]
	s_add_i32 m0, s51, 0x3f00
	v_mfma_f32_16x16x32_bf16 v[52:55], v[80:83], v[104:107], v[52:55]
	global_load_lds_dwordx4 v64, s[46:47] offset:256
	v_mfma_f32_16x16x32_bf16 v[48:51], v[88:91], v[104:107], v[48:51]
	v_mfma_f32_16x16x32_bf16 v[44:47], v[80:83], v[112:115], v[44:47]
	v_mfma_f32_16x16x32_bf16 v[40:43], v[88:91], v[112:115], v[40:43]
	s_add_i32 m0, s51, 0x5f00
	v_mfma_f32_16x16x32_bf16 v[36:39], v[80:83], v[120:123], v[36:39]
	global_load_lds_dwordx4 v66, s[46:47] offset:256
	v_mfma_f32_16x16x32_bf16 v[32:35], v[88:91], v[120:123], v[32:35]
	s_setprio 0
	s_barrier
	s_add_u32 s42, s42, 0x200
	s_addc_u32 s43, s43, 0
	s_add_u32 vcc_lo, vcc_lo, 0x200
	s_addc_u32 vcc_hi, vcc_hi, 0
	s_add_i32 s52, s52, 4
	s_cmp_ge_i32 s52, s33
	s_cbranch_scc0 .LBB0_181
	s_and_b64 vcc, exec, s[10:11]
	s_cbranch_vccz .LBB0_184

.LBB0_184:
	v_mov_b32_e32 v76, v165
	s_add_i32 s7, s70, s77
	v_mbcnt_lo_u32_b32 v76, -1, v76
	v_mbcnt_hi_u32_b32 v78, -1, v76
	v_and_b32_e32 v76, 15, v78
	v_add_u32_e32 v76, s7, v76
	v_ashrrev_i32_e32 v77, 31, v76
	v_lshlrev_b64 v[76:77], 11, v[76:77]
	s_lshl_b32 s42, s50, 7
	v_lshl_add_u64 v[76:77], s[8:9], 0, v[76:77]
	s_ashr_i32 s43, s42, 31
	v_lshl_add_u64 v[76:77], s[42:43], 1, v[76:77]
	v_readlane_b32 s42, v240, 62
	v_ashrrev_i32_e32 v78, 1, v78
	v_readlane_b32 s43, v240, 63
	v_and_b32_e32 v78, -8, v78
	v_ashrrev_i32_e32 v79, 31, v78
	v_lshl_add_u64 v[76:77], v[76:77], 0, s[42:43]
	v_lshl_add_u64 v[76:77], v[78:79], 1, v[76:77]
	s_mov_b32 s7, 0x8000
	v_cvt_pk_bf16_f32 v52, v52, v53
	v_cvt_pk_bf16_f32 v53, v54, v55
	v_cvt_pk_bf16_f32 v54, v48, v49
	v_add_co_u32_e32 v48, vcc, s7, v76
	s_mov_b32 s7, 0x10000
	s_nop 0
	v_addc_co_u32_e32 v49, vcc, 0, v77, vcc
	v_cvt_pk_bf16_f32 v44, v44, v45
	v_cvt_pk_bf16_f32 v45, v46, v47
	v_cvt_pk_bf16_f32 v46, v40, v41
	v_add_co_u32_e32 v40, vcc, s7, v76
	v_cvt_pk_bf16_f32 v36, v36, v37
	v_cvt_pk_bf16_f32 v37, v38, v39
	v_cvt_pk_bf16_f32 v38, v32, v33
	s_mov_b32 s7, 0x40000
	s_nop 0
	v_addc_co_u32_e32 v41, vcc, 0, v77, vcc
	v_add_co_u32_e32 v32, vcc, s75, v76
	v_cvt_pk_bf16_f32 v28, v28, v29
	v_cvt_pk_bf16_f32 v29, v30, v31
	v_cvt_pk_bf16_f32 v30, v24, v25
	v_cvt_pk_bf16_f32 v20, v20, v21
	s_nop 1
	v_addc_co_u32_e32 v33, vcc, 0, v77, vcc
	v_add_co_u32_e32 v24, vcc, s7, v76
	v_cvt_pk_bf16_f32 v21, v22, v23
	v_cvt_pk_bf16_f32 v22, v16, v17
	v_cvt_pk_bf16_f32 v12, v12, v13
	v_cvt_pk_bf16_f32 v13, v14, v15
	s_nop 1
	v_addc_co_u32_e32 v25, vcc, 0, v77, vcc
	v_add_co_u32_e32 v16, vcc, s57, v76
	v_cvt_pk_bf16_f32 v14, v8, v9
	v_cvt_pk_bf16_f32 v4, v4, v5
	v_cvt_pk_bf16_f32 v5, v6, v7
	v_cvt_pk_bf16_f32 v6, v0, v1
	s_nop 1
	v_addc_co_u32_e32 v17, vcc, 0, v77, vcc
	v_add_co_u32_e32 v8, vcc, 0x50000, v76
	v_cvt_pk_bf16_f32 v60, v60, v61
	v_cvt_pk_bf16_f32 v61, v62, v63
	v_cvt_pk_bf16_f32 v62, v56, v57
	v_cvt_pk_bf16_f32 v63, v58, v59
	s_nop 1
	v_addc_co_u32_e32 v9, vcc, 0, v77, vcc
	v_add_co_u32_e32 v0, vcc, 0x58000, v76
	flat_store_dwordx4 v[76:77], v[60:63]
	s_nop 0
	v_addc_co_u32_e32 v1, vcc, 0, v77, vcc
	s_andn2_b64 vcc, exec, s[18:19]
	s_mov_b64 s[18:19], -1
	v_cvt_pk_bf16_f32 v55, v50, v51
	flat_store_dwordx4 v[48:49], v[52:55]
	v_cvt_pk_bf16_f32 v47, v42, v43
	flat_store_dwordx4 v[40:41], v[44:47]
	v_cvt_pk_bf16_f32 v39, v34, v35
	flat_store_dwordx4 v[32:33], v[36:39]
	v_cvt_pk_bf16_f32 v31, v26, v27
	v_cvt_pk_bf16_f32 v23, v18, v19
	v_cvt_pk_bf16_f32 v15, v10, v11
	v_cvt_pk_bf16_f32 v7, v2, v3
	s_cbranch_vccnz .LBB0_173
	s_andn2_b64 vcc, exec, s[82:83]
	s_cbranch_vccnz .LBB0_172
	s_barrier
	s_branch .LBB0_172
